# k22
# speedup vs baseline: 1.0016x; 1.0016x over previous
; #define SBAR() __builtin_amdgcn_sched_barrier(0)
; #define SLOAD(i, k0) do { sr_[i].vs0 = LD8(&Vh[(long)((k0) + sr) * LDQK + sc]); sr_[i].vs1 = LD8(&Vh[(long)((k0) + 32 + sr) * LDQK + sc]); \
;     sr_[i].ks0 = LD8(&Kh[(long)((k0) + sr) * LDQK + sc]); sr_[i].ks1 = LD8(&Kh[(long)((k0) + 32 + sr) * LDQK + sc]); } while (0)
; #define SWRITE(b, i) do { *(bf16x8*)((char*)V_lds + (b) * SHM_V + vst0) = sr_[i].vs0;          \
;     *(bf16x8*)((char*)V_lds + (b) * SHM_V + vst1) = sr_[i].vs1; int kc = sc * 2;               \
;     *(bf16x8*)((char*)K_lds + (b) * SHM_K + KSWZ(sr, kc)) = sr_[i].ks0;                       \
;     *(bf16x8*)((char*)K_lds + (b) * SHM_K + KSWZ(32 + sr, kc)) = sr_[i].ks1; } while (0)
; #define SWAIT() asm volatile("s_waitcnt vmcnt(4)" ::: "memory")
; #define RESC(a) do { if (__any((a) < 1.f)) { if (hi == 0) al_l[r32] = (a); asm volatile("s_waitcnt lgkmcnt(0)" ::: "memory"); \
;     for (int d = 0; d < 4; ++d) for (int r = 0; r < 16; ++r) o[d][r] *= al_l[crow(r, hi)]; } } while (0)
; __device__ __forceinline__ void attn_dense_body(const u16* __restrict__ Qb, const u16* __restrict__ Kh, const u16* __restrict__ Vh,
;                                                 u16* __restrict__ Ob, int seq, char* lds, const float* __restrict__ qgain, const float* __restrict__ ropetab, int t0) {
;     ...
;   for (int j = 1; j + 1 < NT; j += 2) {
;     SBAR(); qkt(pB0, pB1, (u16*)((char*)K_lds + SHM_K), qr, r32, hi);
;     finishSM(pA0, pA1, alA, l_reg, pa0, pa1, pa2, pa3); SBAR();
;     SLOAD(SO, (j + 2) * KVBLK); SBAR();
;     pv_d0(o, vb0, pa0, pa1, pa2, pa3); partialSM(pB0, pB1, m_reg, mnB, alB);
;     __syncthreads(); SWAIT(); SWRITE(0, SE);
;     RESC(alB); __syncthreads();
;     SBAR(); qkt(pA0, pA1, K_lds, qr, r32, hi);
;     finishSM(pB0, pB1, alB, l_reg, pa0, pa1, pa2, pa3); SBAR();
;     if (j + 3 < NT) SLOAD(SE, (j + 3) * KVBLK); SBAR();
;     pv_d0(o, vb0 + (int)SHM_V, pa0, pa1, pa2, pa3); partialSM(pA0, pA1, m_reg, mnA, alA);
;     __syncthreads(); SWAIT(); SWRITE(1, SO);
;     RESC(alA); __syncthreads();
.Lattn_head:
	s_barrier

; #define SWRITE(b, i) do { *(bf16x8*)((char*)V_lds + (b) * SHM_V + vst0) = sr_[i].vs0;          \
;     *(bf16x8*)((char*)V_lds + (b) * SHM_V + vst1) = sr_[i].vs1; int kc = sc * 2;               \
;     *(bf16x8*)((char*)K_lds + (b) * SHM_K + KSWZ(sr, kc)) = sr_[i].ks0;                       \
;     *(bf16x8*)((char*)K_lds + (b) * SHM_K + KSWZ(32 + sr, kc)) = sr_[i].ks1; } while (0)
; #define SWAIT() asm volatile("s_waitcnt vmcnt(4)" ::: "memory")
; #define RESC(a) do { if (__any((a) < 1.f)) { if (hi == 0) al_l[r32] = (a); asm volatile("s_waitcnt lgkmcnt(0)" ::: "memory"); \
;     for (int d = 0; d < 4; ++d) for (int r = 0; r < 16; ++r) o[d][r] *= al_l[crow(r, hi)]; } } while (0)
; __device__ __forceinline__ void partialSM(f32x16& p0, f32x16& p1, float& m_reg, float& mn, float& alpha) {
;   constexpr float C = ASCALE * 1.4426950408889634f;
;   float pmax = p0[0]; for (int r = 1; r < 16; ++r) pmax = fmaxf(pmax, p0[r]); for (int r = 0; r < 16; ++r) pmax = fmaxf(pmax, p1[r]);
;   { auto rr = __builtin_amdgcn_permlane32_swap(__float_as_uint(pmax), __float_as_uint(pmax), false, false);
;     pmax = fmaxf(__uint_as_float(rr[0]), __uint_as_float(rr[1])); }
;   if (__builtin_expect(__all(pmax - m_reg <= ATHR / ASCALE), 1)) { mn = m_reg; alpha = 1.f; }
;   else { mn = fmaxf(m_reg, pmax); alpha = __builtin_amdgcn_exp2f((m_reg - mn) * C); m_reg = mn; }
;   float mnC = -mn * C;
;   for (int r = 0; r < 16; ++r) p0[r] = fmaf(p0[r], C, mnC); for (int r = 0; r < 16; ++r) p1[r] = fmaf(p1[r], C, mnC);
;   for (int r = 0; r < 16; ++r) p0[r] = __builtin_amdgcn_exp2f(p0[r]);
; }
; __device__ __forceinline__ void attn_dense_body(const u16* __restrict__ Qb, const u16* __restrict__ Kh, const u16* __restrict__ Vh,
;                                                 u16* __restrict__ Ob, int seq, char* lds, const float* __restrict__ qgain, const float* __restrict__ ropetab, int t0) {
;     ...
;     pv_d0(o, vb0 + (int)SHM_V, pa0, pa1, pa2, pa3); partialSM(pA0, pA1, m_reg, mnA, alA);
;     __syncthreads(); SWAIT(); SWRITE(1, SO);
;     RESC(alA); __syncthreads();
.LBB0_868:
	v_cndmask_b32_e64 v164, v161, v213, s[10:11]
	v_mul_f32_e32 v150, 0xbe0293ee, v164
	v_mov_b32_e32 v151, v150
	v_fmamk_f32 v80, v80, 0x3e0293ee, v150
	v_fmamk_f32 v81, v81, 0x3e0293ee, v150
	v_fmamk_f32 v82, v82, 0x3e0293ee, v150
	v_fmamk_f32 v83, v83, 0x3e0293ee, v150
	v_fmamk_f32 v84, v84, 0x3e0293ee, v150
	v_fmamk_f32 v85, v85, 0x3e0293ee, v150
	v_fmamk_f32 v86, v86, 0x3e0293ee, v150
	v_fmamk_f32 v87, v87, 0x3e0293ee, v150
	v_fmamk_f32 v88, v88, 0x3e0293ee, v150
	v_fmamk_f32 v89, v89, 0x3e0293ee, v150
	v_fmamk_f32 v90, v90, 0x3e0293ee, v150
	v_fmamk_f32 v91, v91, 0x3e0293ee, v150
	v_fmamk_f32 v92, v92, 0x3e0293ee, v150
	v_fmamk_f32 v93, v93, 0x3e0293ee, v150
	v_fmamk_f32 v94, v94, 0x3e0293ee, v150
	v_fmac_f32_e32 v151, 0x3e0293ee, v95
	v_exp_f32_e32 v175, v80
	v_exp_f32_e32 v216, v81
	v_exp_f32_e32 v161, v82
	v_exp_f32_e32 v213, v83
	v_exp_f32_e32 v162, v84
	v_exp_f32_e32 v174, v85
	v_exp_f32_e32 v163, v86
	v_exp_f32_e32 v173, v87
	v_exp_f32_e32 v170, v88
	v_exp_f32_e32 v172, v89
	v_exp_f32_e32 v169, v90
	v_exp_f32_e32 v171, v91
	v_exp_f32_e32 v166, v92
	v_exp_f32_e32 v168, v93
	v_exp_f32_e32 v165, v94
	v_exp_f32_e32 v167, v151
	v_pk_fma_f32 v[156:157], v[64:65], s[82:83], v[150:151] op_sel_hi:[1,0,0]
	v_add_f32_e32 v64, v210, v211
	v_fmac_f32_e32 v64, v209, v194
	v_add_f32_e32 v194, v214, v215
	s_mov_b64 s[2:3], 0x60000
	v_pk_fma_f32 v[154:155], v[66:67], s[82:83], v[150:151] op_sel_hi:[1,0,0]
	v_pk_fma_f32 v[148:149], v[68:69], s[82:83], v[150:151] op_sel_hi:[1,0,0]
	v_pk_fma_f32 v[146:147], v[70:71], s[82:83], v[150:151] op_sel_hi:[1,0,0]
	v_pk_fma_f32 v[144:145], v[72:73], s[82:83], v[150:151] op_sel_hi:[1,0,0]
	v_pk_fma_f32 v[158:159], v[74:75], s[82:83], v[150:151] op_sel_hi:[1,0,0]
	v_pk_fma_f32 v[152:153], v[76:77], s[82:83], v[150:151] op_sel_hi:[1,0,0]
	v_pk_fma_f32 v[150:151], v[78:79], s[82:83], v[150:151] op_sel_hi:[1,0,0]
	v_fmac_f32_e32 v194, v64, v212
	v_lshl_add_u64 v[180:181], v[180:181], 0, s[2:3]
	s_and_b64 vcc, exec, s[24:25]
	s_waitcnt lgkmcnt(0)
	s_cbranch_vccnz .Lattn_exit
	v_mov_b32_e32 v209, v160
	s_branch .Lattn_head
